# MLA loop: K/V prefetch loads use 32-bit workspace offsets with the base in SGPRs (no 64-bit address adds per tile)
# baseline (speedup 1.0000x reference)
; template <int DQK, int DV, bool BAND> ...
;     ...
;   for (int kt = kt_lo; kt < kt_hi; ++kt) {
;     __syncthreads();
;     if (!PREF) ALOAD(kt);
; #pragma unroll
;     for (int i = 0; i < KCH; ++i) { const int cid = tid + 256 * i, row = cid / KCPR, c8 = cid - row * KCPR; *(u32x4*)&Ks[row * KLD + c8 * 8] = kreg[i]; }
; #pragma unroll
;     for (int i = 0; i < VCH; ++i) { const int cid = tid + 256 * i, row = cid >> 3, c8 = cid & 7;
;       *(u32x2*)&Vs[row * VLD + c8 * 8] = u32x2{vreg[i][0], vreg[i][1]}; *(u32x2*)&Vs[row * VLD + c8 * 8 + 4] = u32x2{vreg[i][2], vreg[i][3]}; }
;     __syncthreads();
;     if (PREF && kt + 1 < kt_hi) ALOAD(kt + 1);
.LBB1_318:
	s_add_i32 s21, s21, 1
	s_cmp_ge_u32 s21, s75
	s_barrier
	s_waitcnt vmcnt(0)
	ds_write_b128 v127, v[106:109]
	ds_write_b128 v128, v[98:101]
	ds_write_b128 v129, v[102:105]
	ds_write2_b64 v130, v[90:91], v[92:93] offset1:1
	ds_write2_b64 v131, v[94:95], v[96:97] offset1:1
	s_waitcnt lgkmcnt(0)
	s_barrier
	s_cbranch_scc1 .LBB1_320
	global_load_dwordx4 v[106:109], v118, s[18:19]
	global_load_dwordx4 v[98:101], v116, s[18:19]
	global_load_dwordx4 v[102:105], v114, s[18:19]
	global_load_dwordx4 v[90:93], v110, s[18:19]
	global_load_dwordx4 v[94:97], v112, s[18:19]

; #define MFMA(a, b, c) __builtin_amdgcn_mfma_f32_32x32x16_bf16((a), (b), (c), 0, 0, 0)
; DI unsigned pk2(float a, float b) { f2_t v = {a, b}; bf2_t r = __builtin_convertvector(v, bf2_t); return __builtin_bit_cast(unsigned, r); }
; DI float xhalf_sum(float x) { const auto rr = __builtin_amdgcn_permlane32_swap(__float_as_uint(x), __float_as_uint(x), false, false); return __uint_as_float(rr[0]) + __uint_as_float(rr[1]); }
; template <int DQK, int DV, bool BAND> ...
;     ...
;       const float m_ref = (m_run == -INFINITY) ? 0.f : m_run;
;       float rs0 = 0.f, rs1 = 0.f;
; #pragma unroll
;       for (int r = 0; r < 16; ++r) { const float e0 = __builtin_amdgcn_exp2f(p0[r] - m_ref), e1 = __builtin_amdgcn_exp2f(p1[r] - m_ref); p0[r] = e0; p1[r] = e1; rs0 += e0; rs1 += e1; }
;       l_run += xhalf_sum(rs0 + rs1);
;       __builtin_amdgcn_s_setprio(1);
; #pragma unroll
;       for (int s = 0; s < 2; ++s) {
;         const u32x4 pu0 = {pk2(p0[8 * s], p0[8 * s + 1]), pk2(p0[8 * s + 2], p0[8 * s + 3]), pk2(p0[8 * s + 4], p0[8 * s + 5]), pk2(p0[8 * s + 6], p0[8 * s + 7])};
;         const u32x4 pu1 = {pk2(p1[8 * s], p1[8 * s + 1]), pk2(p1[8 * s + 2], p1[8 * s + 3]), pk2(p1[8 * s + 4], p1[8 * s + 5]), pk2(p1[8 * s + 6], p1[8 * s + 7])};
; #pragma unroll
;         for (int cb = 0; cb < NCB; ++cb) {
;           const u32x2 lo0 = *(const u32x2*)&Vs[(cb * 32 + r32) * VLD + 16 * s + 4 * hi];
;           const u32x2 hi0 = *(const u32x2*)&Vs[(cb * 32 + r32) * VLD + 16 * s + 4 * hi + 8];
;           const u32x4 v0 = {lo0[0], lo0[1], hi0[0], hi0[1]};
;           o[cb] = MFMA(__builtin_bit_cast(bf16x8, pu0), __builtin_bit_cast(bf16x8, v0), o[cb]);
;         }
; #pragma unroll
;         for (int cb = 0; cb < NCB; ++cb) {
;           const u32x2 lo1 = *(const u32x2*)&Vs[(cb * 32 + r32) * VLD + 32 + 16 * s + 4 * hi];
;           const u32x2 hi1 = *(const u32x2*)&Vs[(cb * 32 + r32) * VLD + 32 + 16 * s + 4 * hi + 8];
;           const u32x4 v1 = {lo1[0], lo1[1], hi1[0], hi1[1]};
;           o[cb] = MFMA(__builtin_bit_cast(bf16x8, pu1), __builtin_bit_cast(bf16x8, v1), o[cb]);
;         }
;       }
;       __builtin_amdgcn_s_setprio(0);
.LBB1_325:
	v_exp_f32_e32 v34, v34
	v_exp_f32_e32 v35, v35
	v_exp_f32_e32 v36, v36
	v_exp_f32_e32 v37, v37
	v_exp_f32_e32 v38, v38
	v_exp_f32_e32 v39, v39
	v_exp_f32_e32 v40, v40
	v_exp_f32_e32 v41, v41
	v_exp_f32_e32 v42, v42
	v_exp_f32_e32 v43, v43
	v_exp_f32_e32 v44, v44
	v_exp_f32_e32 v45, v45
	v_exp_f32_e32 v46, v46
	v_exp_f32_e32 v47, v47
	v_exp_f32_e32 v48, v48
	v_exp_f32_e32 v49, v49
	v_exp_f32_e32 v50, v50
	v_exp_f32_e32 v51, v51
	v_exp_f32_e32 v52, v52
	v_exp_f32_e32 v53, v53
	v_exp_f32_e32 v54, v54
	v_exp_f32_e32 v55, v55
	v_exp_f32_e32 v56, v56
	v_exp_f32_e32 v57, v57
	v_exp_f32_e32 v58, v58
	v_exp_f32_e32 v59, v59
	v_exp_f32_e32 v60, v60
	v_exp_f32_e32 v61, v61
	v_exp_f32_e32 v62, v62
	v_exp_f32_e32 v63, v63
	v_exp_f32_e32 v64, v64
	v_exp_f32_e32 v65, v65
	s_nop 0
	v_pk_add_f32 v[168:169], v[34:35], v[36:37]
	v_pk_add_f32 v[170:171], v[38:39], v[40:41]
	v_pk_add_f32 v[168:169], v[42:43], v[168:169]
	v_pk_add_f32 v[170:171], v[44:45], v[170:171]
	v_pk_add_f32 v[168:169], v[46:47], v[168:169]
	v_pk_add_f32 v[170:171], v[48:49], v[170:171]
	v_pk_add_f32 v[168:169], v[50:51], v[168:169]
	v_pk_add_f32 v[170:171], v[52:53], v[170:171]
	v_pk_add_f32 v[168:169], v[54:55], v[168:169]
	v_pk_add_f32 v[170:171], v[56:57], v[170:171]
	v_pk_add_f32 v[168:169], v[58:59], v[168:169]
	v_pk_add_f32 v[170:171], v[60:61], v[170:171]
	v_pk_add_f32 v[168:169], v[62:63], v[168:169]
	v_pk_add_f32 v[170:171], v[64:65], v[170:171]
	v_pk_add_f32 v[168:169], v[168:169], v[170:171]
	s_nop 0
	v_add_f32_e32 v168, v168, v169
	v_mov_b32_e32 v169, v168
	s_nop 1
	v_permlane32_swap_b32_e32 v168, v169
	v_add_f32_e32 v168, v168, v169
	v_add_f32_e32 v126, v126, v168
	v_cvt_pk_bf16_f32 v34, v34, v35
	v_cvt_pk_bf16_f32 v35, v36, v37
	v_cvt_pk_bf16_f32 v36, v38, v39
	v_cvt_pk_bf16_f32 v37, v40, v41
	v_cvt_pk_bf16_f32 v38, v42, v43
	v_cvt_pk_bf16_f32 v39, v44, v45
	v_cvt_pk_bf16_f32 v40, v46, v47
	v_cvt_pk_bf16_f32 v41, v48, v49
	v_cvt_pk_bf16_f32 v50, v50, v51
	v_cvt_pk_bf16_f32 v51, v52, v53
	v_cvt_pk_bf16_f32 v52, v54, v55
	v_cvt_pk_bf16_f32 v53, v56, v57
	v_cvt_pk_bf16_f32 v54, v58, v59
	v_cvt_pk_bf16_f32 v55, v60, v61
	v_cvt_pk_bf16_f32 v56, v62, v63
	v_cvt_pk_bf16_f32 v57, v64, v65
	s_setprio 1
	s_waitcnt lgkmcnt(0)
	v_mfma_f32_32x32x16_bf16 v[2:17], v[34:37], v[208:211], v[2:17]
	v_mfma_f32_32x32x16_bf16 v[18:33], v[34:37], v[212:215], v[18:33]
	v_mfma_f32_32x32x16_bf16 v[2:17], v[50:53], v[216:219], v[2:17]
	v_mfma_f32_32x32x16_bf16 v[18:33], v[50:53], v[220:223], v[18:33]
	v_mfma_f32_32x32x16_bf16 v[2:17], v[38:41], v[224:227], v[2:17]
	v_mfma_f32_32x32x16_bf16 v[18:33], v[38:41], v[228:231], v[18:33]
	v_mfma_f32_32x32x16_bf16 v[2:17], v[54:57], v[232:235], v[2:17]
	v_mfma_f32_32x32x16_bf16 v[18:33], v[54:57], v[236:239], v[18:33]
	s_setprio 0
	v_add_u32_e32 v110, s8, v110
	v_add_u32_e32 v112, s8, v112
	v_add_u32_e32 v114, s10, v114
	v_add_u32_e32 v116, s10, v116
	s_cmp_eq_u32 s75, s21
	v_add_u32_e32 v118, s10, v118
	s_cbranch_scc1 .LBB1_327
	v_mov_b32_e32 v133, v0
	s_branch .LBB1_318
